# v23 plus attention loops: canonicalising v_max in front of max(z,0) folded away (z is an MFMA result), 32 VALU instructions fewer per key block
# baseline (speedup 1.0000x reference)
; #define LAS __attribute__((address_space(3)))
; #define MFMA16(a, b, c) __builtin_amdgcn_mfma_f32_16x16x32_bf16((a), (b), (c), 0, 0, 0)
; __device__ __forceinline__ void attn_phase(Frame& F, bf16* OZ) {
;     ...
;         const int nkb = smp ? 17 : 2 * qb + 2;
;         ATT_LOAD_KV(0);
;         __syncthreads();
;         const bool active = wave * 16 < nq;
;         bf16x8 qf[4];
; #pragma unroll
;         for (int ks = 0; ks < 4; ++ks) qf[ks] = *(const LAS bf16x8*)(L + QS + (wave * 16 + l15) * ST_ + (32 * ks + 8 * g4) * 2);
;         f32x4 oacc[8];
; #pragma unroll
;         for (int i = 0; i < 8; ++i) oacc[i] = (f32x4){0.f, 0.f, 0.f, 0.f};
;         float carry = 0.f;
;         const int tq = wave * 16 + l15, tpos = smp ? 1024 + tq : qrow0 + tq;
;         for (int kb = 0; kb < nkb; ++kb) {
;             const int spos0 = !smp ? (2 * qb + 1 - kb) * 64 : (kb == 0 ? 1024 : 1024 - 64 * kb), nvalid = (smp && kb == 0) ? 16 : 64;
;             if (kb > 0) { ATT_LOAD_KV(kb); __syncthreads(); }
;             bool done = true;
;             const bool none_visible = spos0 > __builtin_amdgcn_readfirstlane(tpos - l15) + 14;
;             if (active && none_visible) done = false;
;             if (active && !none_visible) {
;                 f32x4 sc[4];
; #pragma unroll
;                 for (int sb = 0; sb < 4; ++sb) { sc[sb] = (f32x4){0.f, 0.f, 0.f, 0.f};
; #pragma unroll
;                     for (int ks = 0; ks < 4; ++ks) { const bf16x8 a = *(const LAS bf16x8*)(L + KS + (16 * sb + l15) * ST_ + (32 * ks + 8 * g4) * 2); sc[sb] = MFMA16(a, qf[ks], sc[sb]); } }
;                 float lk[4][4], tsum[4], above[4], ttot[4];
; #pragma unroll
;                 for (int sb = 0; sb < 4; ++sb) { tsum[sb] = 0.f;
; #pragma unroll
;                     for (int e = 0; e < 4; ++e) { const int s = 16 * sb + 4 * g4 + e; const float z = sc[sb][e]; const bool vis = (s < nvalid) && (spos0 + s < tpos);
;                         const float sp = fmaxf(z, 0.f) + __logf(1.0f + __expf(-fabsf(z)));
;                         lk[sb][e] = vis ? -sp : 0.f; sc[sb][e] = vis ? z - sp : -1e30f; tsum[sb] += lk[sb][e]; }
.LBB0_1895:
	s_lshl_b32 s1, s19, 1
	s_add_i32 s19, s1, 2
	s_and_b64 s[2:3], s[38:39], exec
	s_cselect_b32 s36, 17, s19
	s_cmp_lt_u32 s33, s18
	s_cselect_b64 s[40:41], -1, 0
	s_cmp_lt_i32 s36, 1
	s_waitcnt vmcnt(0)
	ds_write_b128 v145, v[10:13] offset:52224
	s_waitcnt lgkmcnt(0)
	s_barrier
	s_cbranch_scc1 .LBB0_1898
	v_add_u32_e32 v90, s0, v87
	s_lshl_b32 s0, s1, 6
	s_xor_b64 s[42:43], s[40:41], -1
	s_or_b32 s2, s0, 64
	ds_read_b128 v[10:13], v143
	ds_read_b128 v[14:17], v143 offset:64
	ds_read_b128 v[18:21], v143 offset:128
	ds_read_b128 v[22:25], v143 offset:192
	v_sub_u32_e32 v150, v90, v83
	s_and_b64 s[0:1], s[38:39], exec
	v_readfirstlane_b32 s0, v150
	s_cselect_b32 s2, 0x400, s2
	s_add_i32 s0, s0, 14
	s_cmp_gt_i32 s2, s0
	s_cselect_b64 s[0:1], -1, 0
	s_or_b64 s[18:19], s[42:43], s[0:1]
	s_and_b64 vcc, exec, s[18:19]
	s_cbranch_vccnz .LBB0_1899
	ds_read_b128 v[26:29], v146 offset:34816
	ds_read_b128 v[30:33], v146 offset:34880
	ds_read_b128 v[34:37], v146 offset:39168
	ds_read_b128 v[38:41], v146 offset:39232
	ds_read_b128 v[42:45], v146 offset:34944
	v_and_b32_e32 v4, 64, v147
	s_waitcnt lgkmcnt(4)
	v_mfma_f32_16x16x32_bf16 v[26:29], v[26:29], v[10:13], 0
	v_xor_b32_e32 v3, 16, v147
	v_add_u32_e32 v4, 64, v4
	v_cmp_lt_i32_e32 vcc, v3, v4
	s_waitcnt lgkmcnt(3)
	v_mfma_f32_16x16x32_bf16 v[26:29], v[30:33], v[14:17], v[26:29]
	ds_read_b128 v[30:33], v146 offset:35008
	v_cndmask_b32_e32 v3, v147, v3, vcc
	v_lshlrev_b32_e32 v47, 2, v3
	s_waitcnt lgkmcnt(1)
	v_mfma_f32_16x16x32_bf16 v[26:29], v[42:45], v[18:21], v[26:29]
	ds_read_b128 v[42:45], v146 offset:39296
	v_xor_b32_e32 v3, 32, v147
	v_cmp_lt_i32_e32 vcc, v3, v4
	v_mfma_f32_16x16x32_bf16 v[34:37], v[34:37], v[10:13], 0
	s_and_b64 s[0:1], s[38:39], exec
	v_cndmask_b32_e32 v3, v147, v3, vcc
	v_lshlrev_b32_e32 v46, 2, v3
	s_waitcnt lgkmcnt(1)
	v_mfma_f32_16x16x32_bf16 v[30:33], v[30:33], v[22:25], v[26:29]
	v_xor_b32_e32 v3, 48, v147
	v_cmp_lt_i32_e32 vcc, v3, v4
	s_cselect_b32 s3, 16, 64
	ds_read_b128 v[26:29], v146 offset:39360
	v_mfma_f32_16x16x32_bf16 v[34:37], v[38:41], v[14:17], v[34:37]
	ds_read_b128 v[38:41], v146 offset:43520
	ds_read_b128 v[48:51], v146 offset:43584
	ds_read_b128 v[52:55], v146 offset:43648
	ds_read_b128 v[56:59], v146 offset:43712
	v_mul_f32_e64 v4, |v30|, s49
	v_exp_f32_e32 v4, v4
	s_waitcnt lgkmcnt(5)
	v_mfma_f32_16x16x32_bf16 v[34:37], v[42:45], v[18:21], v[34:37]
	v_cndmask_b32_e32 v3, v147, v3, vcc
	ds_read_b128 v[42:45], v146 offset:47872
	ds_read_b128 v[60:63], v146 offset:47936
	ds_read_b128 v[64:67], v146 offset:48000
	ds_read_b128 v[68:71], v146 offset:48064
	v_add_f32_e32 v4, 1.0, v4
	s_waitcnt lgkmcnt(8)
	v_mfma_f32_16x16x32_bf16 v[26:29], v[26:29], v[22:25], v[34:37]
	s_waitcnt lgkmcnt(7)
	v_mfma_f32_16x16x32_bf16 v[34:37], v[38:41], v[10:13], 0
	v_log_f32_e32 v4, v4
	s_waitcnt lgkmcnt(6)
	v_mfma_f32_16x16x32_bf16 v[34:37], v[48:51], v[14:17], v[34:37]
	v_max_f32_e32 v5, 0, v30
	s_waitcnt lgkmcnt(5)
	v_mfma_f32_16x16x32_bf16 v[34:37], v[52:55], v[18:21], v[34:37]
	v_lshlrev_b32_e32 v48, 2, v3
	v_or_b32_e32 v3, s2, v86
	s_waitcnt lgkmcnt(4)
	v_mfma_f32_16x16x32_bf16 v[38:41], v[56:59], v[22:25], v[34:37]
	s_waitcnt lgkmcnt(3)
	v_mfma_f32_16x16x32_bf16 v[34:37], v[42:45], v[10:13], 0
	v_mul_f32_e32 v42, 0x3f317217, v4
	v_fma_f32 v42, v4, s53, -v42
	v_fmac_f32_e32 v42, 0x3377d1cf, v4
	v_fma_f32 v4, v4, s53, v42
	v_add_f32_e32 v4, v5, v4
	v_sub_f32_e32 v5, v30, v4
	v_mul_f32_e64 v30, |v31|, s49
	v_exp_f32_e32 v30, v30
	v_sub_f32_e32 v50, 0, v4
	v_cmp_lt_i32_e32 vcc, v3, v90
	v_mul_f32_e64 v43, |v33|, s49
	v_add_f32_e32 v4, 1.0, v30
	v_cndmask_b32_e32 v3, v149, v5, vcc
	v_log_f32_e32 v4, v4
	v_max_f32_e32 v30, 0, v31
	v_or_b32_e32 v5, s2, v98
	v_exp_f32_e32 v43, v43
	v_mul_f32_e32 v42, 0x3f317217, v4
	v_fma_f32 v42, v4, s53, -v42
	v_fmac_f32_e32 v42, 0x3377d1cf, v4
	v_fma_f32 v4, v4, s53, v42
	v_mul_f32_e64 v52, |v38|, s49
	v_exp_f32_e32 v52, v52
	v_add_f32_e32 v30, v30, v4
	v_mul_f32_e64 v4, |v32|, s49
	v_exp_f32_e32 v42, v4
	v_cmp_lt_i32_e64 s[0:1], v5, v90
	v_sub_f32_e32 v5, v31, v30
	v_add_f32_e32 v52, 1.0, v52
	v_cndmask_b32_e64 v49, v149, v5, s[0:1]
	v_add_f32_e32 v5, 1.0, v42
	v_cndmask_b32_e64 v4, 0, -v30, s[0:1]
	s_waitcnt lgkmcnt(2)
	v_mfma_f32_16x16x32_bf16 v[34:37], v[60:63], v[14:17], v[34:37]
	v_or_b32_e32 v31, s2, v88
	v_log_f32_e32 v5, v5
	v_max_f32_e32 v42, 0, v32
	s_waitcnt lgkmcnt(1)
	v_mfma_f32_16x16x32_bf16 v[34:37], v[64:67], v[18:21], v[34:37]
	v_mul_f32_e32 v30, 0x3f317217, v5
	v_fma_f32 v30, v5, s53, -v30
	v_fmac_f32_e32 v30, 0x3377d1cf, v5
	v_fma_f32 v5, v5, s53, v30
	s_waitcnt lgkmcnt(0)
; __device__ __forceinline__ void attn_phase(Frame& F, bf16* OZ) {
;     ...
;                     for (int e = 0; e < 4; ++e) { const int s = 16 * sb + 4 * g4 + e; const float z = sc[sb][e]; const bool vis = (s < nvalid) && (spos0 + s < tpos);
;                         const float sp = fmaxf(z, 0.f) + __logf(1.0f + __expf(-fabsf(z)));
;                         lk[sb][e] = vis ? -sp : 0.f; sc[sb][e] = vis ? z - sp : -1e30f; tsum[sb] += lk[sb][e]; }
;                     const float v1 = __shfl_xor(tsum[sb], 16), v2 = __shfl_xor(tsum[sb], 32), v3 = __shfl_xor(tsum[sb], 48);
;                     above[sb] = ((g4 ^ 1) > g4 ? v1 : 0.f) + ((g4 ^ 2) > g4 ? v2 : 0.f) + ((g4 ^ 3) > g4 ? v3 : 0.f);
;                     ttot[sb] = (tsum[sb] + v1) + (v2 + v3); }
	v_mfma_f32_16x16x32_bf16 v[34:37], v[68:71], v[22:25], v[34:37]
	v_mov_b32_e32 v44, v5
	v_add_f32_e32 v5, 1.0, v43
	v_max_f32_e32 v43, 0, v33
	v_log_f32_e32 v5, v5
	v_or_b32_e32 v30, s2, v99
	v_mul_f32_e32 v45, 0x3f317217, v5
	v_fma_f32 v45, v5, s53, -v45
	v_fmac_f32_e32 v45, 0x3377d1cf, v5
	v_fma_f32 v5, v5, s53, v45
	s_nop 1
	v_add_f32_e32 v5, v43, v5
	v_cmp_lt_i32_e64 s[0:1], v30, v90
	s_nop 1
	v_cndmask_b32_e64 v30, 0, -v5, s[0:1]
	v_sub_f32_e32 v5, v33, v5
	v_mul_f32_e64 v33, |v26|, s49
	v_exp_f32_e32 v43, v33
	v_cndmask_b32_e64 v33, v149, v5, s[0:1]
	v_or_b32_e32 v5, s2, v100
	v_cmp_lt_i32_e64 s[20:21], v5, v90
	v_add_f32_e32 v43, 1.0, v43
	v_max_f32_e32 v5, 0, v26
	v_log_f32_e32 v43, v43
	v_cmp_gt_u32_e64 s[0:1], s3, v100
	s_and_b64 s[0:1], s[0:1], s[20:21]
	v_mul_f32_e32 v45, 0x3f317217, v43
	v_fma_f32 v45, v43, s53, -v45
	v_fmac_f32_e32 v45, 0x3377d1cf, v43
	v_fma_f32 v43, v43, s53, v45
	s_nop 1
	v_add_f32_e32 v5, v5, v43
	v_mul_f32_e64 v43, |v27|, s49
	v_exp_f32_e32 v43, v43
	v_or_b32_e32 v45, s2, v101
	v_sub_f32_e32 v26, v26, v5
	v_sub_f32_e32 v5, 0, v5
	v_add_f32_e32 v43, 1.0, v43
	v_cmp_lt_i32_e64 s[20:21], v45, v90
	v_log_f32_e32 v43, v43
	v_cndmask_b32_e64 v26, v149, v26, s[0:1]
	v_cndmask_b32_e64 v5, 0, v5, s[0:1]
	v_cmp_gt_u32_e64 s[0:1], s3, v101
	v_mul_f32_e32 v51, 0x3f317217, v43
	v_fma_f32 v51, v43, s53, -v51
	v_fmac_f32_e32 v51, 0x3377d1cf, v43
	v_fma_f32 v43, v43, s53, v51
	v_max_f32_e32 v45, 0, v27
	s_and_b64 s[0:1], s[0:1], s[20:21]
	v_add_f32_e32 v43, v45, v43
	v_cndmask_b32_e64 v58, 0, -v43, s[0:1]
	v_sub_f32_e32 v27, v27, v43
	v_mul_f32_e64 v43, |v28|, s49
	v_exp_f32_e32 v43, v43
	v_or_b32_e32 v45, s2, v1
	v_cmp_lt_i32_e64 s[20:21], v45, v90
	v_add_f32_e32 v43, 1.0, v43
	v_max_f32_e32 v45, 0, v28
	v_cndmask_b32_e64 v27, v149, v27, s[0:1]
	v_log_f32_e32 v43, v43
	v_cmp_gt_u32_e64 s[0:1], s3, v1
	v_add_f32_e32 v5, v58, v5
	v_mul_f32_e32 v51, 0x3f317217, v43
	v_fma_f32 v51, v43, s53, -v51
	v_fmac_f32_e32 v51, 0x3377d1cf, v43
	v_fma_f32 v43, v43, s53, v51
	s_nop 1
	v_add_f32_e32 v51, v45, v43
	v_mul_f32_e64 v43, |v29|, s49
	v_exp_f32_e32 v43, v43
	v_sub_f32_e32 v28, v28, v51
	s_and_b64 s[18:19], s[0:1], s[20:21]
	v_cndmask_b32_e64 v59, v149, v28, s[18:19]
	v_add_f32_e32 v43, 1.0, v43
	v_cmp_gt_f32_e64 s[22:23], s52, v43
	v_or_b32_e32 v28, s2, v75
	v_cmp_lt_i32_e64 s[20:21], v28, v90
	v_cndmask_b32_e64 v45, 0, 32, s[22:23]
	v_ldexp_f32 v43, v43, v45
	v_log_f32_e32 v45, v43
	v_max_f32_e32 v43, 0, v29
	v_cmp_gt_u32_e64 s[0:1], s3, v75
	v_mul_f32_e32 v28, 0x3f317217, v45
	v_fma_f32 v28, v45, s53, -v28
	v_fmac_f32_e32 v28, 0x3377d1cf, v45
	v_fmac_f32_e32 v28, 0x3f317217, v45
	v_cmp_lt_f32_e64 s[24:25], |v45|, s54
	s_nop 1
	v_cndmask_b32_e64 v28, v45, v28, s[24:25]
	v_cndmask_b32_e64 v45, 0, v148, s[22:23]
	v_sub_f32_e32 v45, v28, v45
	v_log_f32_e32 v52, v52
	v_or_b32_e32 v28, s2, v102
	v_cmp_lt_i32_e64 s[26:27], v28, v90
	v_mul_f32_e32 v53, 0x3f317217, v52
	v_fma_f32 v53, v52, s53, -v53
	v_fmac_f32_e32 v53, 0x3377d1cf, v52
	v_fma_f32 v52, v52, s53, v53
	v_max_f32_e32 v28, 0, v38
	v_cmp_gt_u32_e64 s[22:23], s3, v102
	v_add_f32_e32 v28, v28, v52
	v_sub_f32_e32 v38, v38, v28
	s_and_b64 s[22:23], s[22:23], s[26:27]
	v_cndmask_b32_e64 v66, v149, v38, s[22:23]
	v_mul_f32_e64 v38, |v39|, s49
	v_exp_f32_e32 v38, v38
	v_or_b32_e32 v52, s2, v103
	v_sub_f32_e32 v28, 0, v28
	v_cmp_lt_i32_e64 s[26:27], v52, v90
	v_add_f32_e32 v38, 1.0, v38
	v_cndmask_b32_e64 v28, 0, v28, s[22:23]
	v_log_f32_e32 v38, v38
	v_cmp_gt_u32_e64 s[22:23], s3, v103
	v_max_f32_e32 v52, 0, v39
	s_and_b64 s[22:23], s[22:23], s[26:27]
	v_mul_f32_e32 v53, 0x3f317217, v38
	v_fma_f32 v53, v38, s53, -v53
	v_fmac_f32_e32 v53, 0x3377d1cf, v38
	v_fma_f32 v38, v38, s53, v53
	s_nop 1
	v_add_f32_e32 v38, v52, v38
	v_cndmask_b32_e64 v67, 0, -v38, s[22:23]
	v_sub_f32_e32 v38, v39, v38
	v_cndmask_b32_e64 v62, v149, v38, s[22:23]
	v_mul_f32_e64 v38, |v40|, s49
	v_exp_f32_e32 v38, v38
	v_or_b32_e32 v39, s2, v104
	v_cmp_lt_i32_e64 s[26:27], v39, v90
	v_add_f32_e32 v38, 1.0, v38
	v_cmp_gt_u32_e64 s[22:23], s3, v104
	v_max_f32_e32 v39, 0, v40
	v_log_f32_e32 v38, v38
	s_and_b64 s[22:23], s[22:23], s[26:27]
	v_add_f32_e32 v28, v67, v28
	v_mul_f32_e32 v52, 0x3f317217, v38
	v_fma_f32 v52, v38, s53, -v52
	v_fmac_f32_e32 v52, 0x3377d1cf, v38
	v_fma_f32 v38, v38, s53, v52
	s_nop 1
	v_add_f32_e32 v38, v39, v38
	v_cndmask_b32_e64 v60, 0, -v38, s[22:23]
	v_sub_f32_e32 v38, v40, v38
	v_cndmask_b32_e64 v61, v149, v38, s[22:23]
	v_mul_f32_e64 v38, |v41|, s49
	v_exp_f32_e32 v38, v38
	v_or_b32_e32 v39, s2, v105
	v_cmp_lt_i32_e64 s[26:27], v39, v90
	v_add_f32_e32 v38, 1.0, v38
	v_cmp_gt_u32_e64 s[22:23], s3, v105
	v_max_f32_e32 v39, 0, v41
	v_log_f32_e32 v38, v38
	s_and_b64 s[22:23], s[22:23], s[26:27]
	v_add_f32_e32 v28, v60, v28
	v_mul_f32_e32 v40, 0x3f317217, v38
	v_fma_f32 v40, v38, s53, -v40
	v_fmac_f32_e32 v40, 0x3377d1cf, v38
	v_fma_f32 v38, v38, s53, v40
	s_nop 1
	v_add_f32_e32 v40, v39, v38
	v_cndmask_b32_e64 v63, 0, -v40, s[22:23]
	v_add_f32_e32 v38, v63, v28
	v_sub_f32_e32 v28, v41, v40
	v_cndmask_b32_e64 v64, v149, v28, s[22:23]
	v_mul_f32_e64 v28, |v34|, s49
	v_exp_f32_e32 v28, v28
	ds_bpermute_b32 v39, v46, v38
	ds_bpermute_b32 v52, v47, v38
	ds_bpermute_b32 v53, v48, v38
	v_add_f32_e32 v28, 1.0, v28
	s_waitcnt lgkmcnt(2)
	v_cndmask_b32_e64 v40, 0, v39, s[6:7]
	v_cmp_gt_u32_e64 s[22:23], s3, v106
	v_log_f32_e32 v28, v28
	s_waitcnt lgkmcnt(0)
; __device__ __forceinline__ void attn_phase(Frame& F, bf16* OZ) {
;     ...
;                     for (int e = 0; e < 4; ++e) { const int s = 16 * sb + 4 * g4 + e; const float z = sc[sb][e]; const bool vis = (s < nvalid) && (spos0 + s < tpos);
;                         const float sp = fmaxf(z, 0.f) + __logf(1.0f + __expf(-fabsf(z)));
;                         lk[sb][e] = vis ? -sp : 0.f; sc[sb][e] = vis ? z - sp : -1e30f; tsum[sb] += lk[sb][e]; }
;                     const float v1 = __shfl_xor(tsum[sb], 16), v2 = __shfl_xor(tsum[sb], 32), v3 = __shfl_xor(tsum[sb], 48);
;                     above[sb] = ((g4 ^ 1) > g4 ? v1 : 0.f) + ((g4 ^ 2) > g4 ? v2 : 0.f) + ((g4 ^ 3) > g4 ? v3 : 0.f);
;                     ttot[sb] = (tsum[sb] + v1) + (v2 + v3); }
;                 float after = carry;
; #pragma unroll
;     ...
; #pragma unroll
;                     for (int e = 3; e >= 0; --e) { const float w = __expf(sc[sb][e] + run); run += lk[sb][e]; sc[sb][e] = w; }
;                     after += ttot[sb]; }
	v_pk_add_f32 v[38:39], v[38:39], v[52:53]
	v_cndmask_b32_e64 v54, 0, v52, s[4:5]
	v_pk_add_f32 v[38:39], v[38:39], v[38:39] op_sel_hi:[0,1]
	v_mul_f32_e32 v41, 0x3f317217, v28
	v_fma_f32 v41, v28, s53, -v41
	v_fmac_f32_e32 v41, 0x3377d1cf, v28
	v_or_b32_e32 v38, s2, v106
	v_fma_f32 v28, v28, s53, v41
	v_cmp_lt_i32_e64 s[26:27], v38, v90
	v_max_f32_e32 v38, 0, v34
	v_add_f32_e32 v28, v38, v28
	v_sub_f32_e32 v34, v34, v28
	s_and_b64 s[22:23], s[22:23], s[26:27]
	v_cndmask_b32_e64 v52, v149, v34, s[22:23]
	v_mul_f32_e64 v34, |v35|, s49
	v_exp_f32_e32 v34, v34
	v_or_b32_e32 v38, s2, v107
	v_sub_f32_e32 v28, 0, v28
	v_cmp_lt_i32_e64 s[26:27], v38, v90
	v_add_f32_e32 v34, 1.0, v34
	v_cndmask_b32_e64 v28, 0, v28, s[22:23]
	v_log_f32_e32 v34, v34
	v_cmp_gt_u32_e64 s[22:23], s3, v107
	v_max_f32_e32 v38, 0, v35
	s_and_b64 s[22:23], s[22:23], s[26:27]
	v_mul_f32_e32 v41, 0x3f317217, v34
	v_fma_f32 v41, v34, s53, -v41
	v_fmac_f32_e32 v41, 0x3377d1cf, v34
	v_fma_f32 v34, v34, s53, v41
	v_cndmask_b32_e64 v56, 0, v53, s[8:9]
	s_nop 0
	v_add_f32_e32 v34, v38, v34
	v_cndmask_b32_e64 v53, 0, -v34, s[22:23]
	v_sub_f32_e32 v34, v35, v34
	v_cndmask_b32_e64 v38, v149, v34, s[22:23]
	v_mul_f32_e64 v34, |v36|, s49
	v_exp_f32_e32 v34, v34
	v_or_b32_e32 v35, s2, v108
	v_cmp_lt_i32_e64 s[26:27], v35, v90
	v_add_f32_e32 v34, 1.0, v34
	v_cmp_gt_u32_e64 s[22:23], s3, v108
	v_max_f32_e32 v35, 0, v36
	v_log_f32_e32 v34, v34
	s_and_b64 s[22:23], s[22:23], s[26:27]
	v_add_f32_e32 v28, v53, v28
	v_mul_f32_e32 v41, 0x3f317217, v34
	v_fma_f32 v41, v34, s53, -v41
	v_fmac_f32_e32 v41, 0x3377d1cf, v34
	v_fma_f32 v34, v34, s53, v41
	s_nop 1
	v_add_f32_e32 v34, v35, v34
	v_cndmask_b32_e64 v41, 0, -v34, s[22:23]
	v_sub_f32_e32 v34, v36, v34
	v_cndmask_b32_e64 v55, v149, v34, s[22:23]
	v_mul_f32_e64 v34, |v37|, s49
	v_exp_f32_e32 v34, v34
	v_or_b32_e32 v35, s2, v109
	v_cmp_lt_i32_e64 s[26:27], v35, v90
	v_add_f32_e32 v34, 1.0, v34
	v_cmp_gt_u32_e64 s[22:23], s3, v109
	v_max_f32_e32 v35, 0, v37
	v_log_f32_e32 v34, v34
	s_and_b64 s[22:23], s[22:23], s[26:27]
	v_add_f32_e32 v28, v41, v28
	v_mul_f32_e32 v36, 0x3f317217, v34
	v_fma_f32 v36, v34, s53, -v36
	v_fmac_f32_e32 v36, 0x3377d1cf, v34
	v_fma_f32 v34, v34, s53, v36
	s_nop 1
	v_add_f32_e32 v57, v35, v34
	v_cndmask_b32_e64 v65, 0, -v57, s[22:23]
	v_add_f32_e32 v34, v65, v28
	ds_bpermute_b32 v35, v46, v34
	ds_bpermute_b32 v36, v47, v34
	v_sub_f32_e32 v28, v37, v57
	ds_bpermute_b32 v37, v48, v34
	v_cndmask_b32_e64 v28, v149, v28, s[22:23]
	s_waitcnt lgkmcnt(2)
	v_cndmask_b32_e64 v57, 0, v35, s[6:7]
	s_waitcnt lgkmcnt(1)
	v_cndmask_b32_e64 v68, 0, v36, s[4:5]
	v_add_f32_e32 v57, v68, v57
	s_waitcnt lgkmcnt(0)
	v_cndmask_b32_e64 v68, 0, v37, s[8:9]
	v_add_f32_e32 v57, v57, v68
	v_pk_add_f32 v[34:35], v[34:35], v[36:37]
	v_add_f32_e32 v36, 0, v57
	v_add_f32_e32 v28, v28, v36
	v_mul_f32_e32 v28, 0x3fb8aa3b, v28
	v_exp_f32_e32 v73, v28
	v_add_f32_e32 v28, v65, v36
	v_add_f32_e32 v36, v55, v28
	v_mul_f32_e32 v36, 0x3fb8aa3b, v36
	v_exp_f32_e32 v92, v36
	v_pk_add_f32 v[36:37], v[42:43], v[44:45]
	v_cmp_lt_i32_e64 s[22:23], v31, v90
	v_cndmask_b32_e64 v43, 0, -v51, s[18:19]
	v_cndmask_b32_e32 v42, 0, v50, vcc
	s_and_b64 vcc, s[0:1], s[20:21]
	v_pk_add_f32 v[44:45], v[42:43], v[4:5]
	v_cndmask_b32_e64 v51, 0, -v37, vcc
	v_cndmask_b32_e64 v50, 0, -v36, s[22:23]
	v_pk_add_f32 v[44:45], v[50:51], v[44:45]
	ds_bpermute_b32 v31, v47, v45
	v_add_f32_e32 v65, v41, v28
	v_add_f32_e32 v28, v38, v65
	v_mul_f32_e32 v28, 0x3fb8aa3b, v28
	v_mov_b32_e32 v55, v34
	v_mov_b32_e32 v41, v35
	v_exp_f32_e32 v72, v28
	v_sub_f32_e32 v28, v32, v36
	v_pk_add_f32 v[34:35], v[54:55], v[40:41]
	v_mov_b32_e32 v57, v2
	s_waitcnt lgkmcnt(0)
	v_pk_add_f32 v[40:41], v[30:31], v[44:45]
	v_cndmask_b32_e64 v32, v149, v28, s[22:23]
	v_pk_add_f32 v[34:35], v[34:35], v[56:57]
	ds_bpermute_b32 v28, v47, v40
	ds_bpermute_b32 v38, v46, v40
	v_add_f32_e32 v5, v34, v35
	ds_bpermute_b32 v34, v48, v40
	v_sub_f32_e32 v29, v29, v37
	s_waitcnt lgkmcnt(2)
	v_cndmask_b32_e64 v36, 0, v28, s[4:5]
	s_waitcnt lgkmcnt(1)
	v_cndmask_b32_e64 v42, 0, v38, s[6:7]
	v_add_f32_e32 v36, v36, v42
	s_waitcnt lgkmcnt(0)
	v_cndmask_b32_e64 v42, 0, v34, s[8:9]
	v_add_f32_e32 v36, v36, v42
	ds_bpermute_b32 v42, v46, v45
	ds_bpermute_b32 v37, v48, v45
	v_cndmask_b32_e32 v44, v149, v29, vcc
	v_cndmask_b32_e64 v29, 0, v31, s[4:5]
	v_pk_add_f32 v[34:35], v[38:39], v[34:35]
	s_waitcnt lgkmcnt(1)
; __device__ __forceinline__ unsigned pk2(float lo, float hi) { const cvt_f2 v = {lo, hi}; const cvt_b2 r = __builtin_convertvector(v, cvt_b2); return __builtin_bit_cast(unsigned, r); }
; #define MFMA16(a, b, c) __builtin_amdgcn_mfma_f32_16x16x32_bf16((a), (b), (c), 0, 0, 0)
; __device__ __forceinline__ void attn_phase(Frame& F, bf16* OZ) {
;     ...
; #pragma unroll
;                     for (int e = 3; e >= 0; --e) { const float w = __expf(sc[sb][e] + run); run += lk[sb][e]; sc[sb][e] = w; }
;                     after += ttot[sb]; }
;                 carry = after;
; #pragma unroll
;                 for (int kk = 0; kk < 2; ++kk) { v4u pkd; pkd.x = pk2(sc[2 * kk][0], sc[2 * kk][1]); pkd.y = pk2(sc[2 * kk][2], sc[2 * kk][3]); pkd.z = pk2(sc[2 * kk + 1][0], sc[2 * kk + 1][1]); pkd.w = pk2(sc[2 * kk + 1][2], sc[2 * kk + 1][3]);
;                     const bf16x8 pf = __builtin_bit_cast(bf16x8, pkd);
; #pragma unroll
;                     for (int dh = 0; dh < 2; ++dh) { unsigned aa[4]; bf16x8 vf[4];
; #pragma unroll
;                         for (int i = 0; i < 4; ++i) aa[i] = F.lds0 + VS + (32 * kk + 4 * g4 + q) * ST_ + (32 * (2 * dh + (i >> 1)) + 8 * p + 4 * (i & 1)) * 2;
;                         tr_read_x4(aa, 16 * ST_, vf);
; #pragma unroll
;                         for (int i = 0; i < 4; ++i) oacc[4 * dh + i] = MFMA16(vf[i], pf, oacc[4 * dh + i]); } }
;                 done = __all(carry < ATT_THR);
	v_cndmask_b32_e64 v31, 0, v42, s[6:7]
	v_add_f32_e32 v29, v29, v31
	s_waitcnt lgkmcnt(0)
	v_cndmask_b32_e64 v31, 0, v37, s[8:9]
	v_add_f32_e32 v31, v29, v31
	v_add_f32_e32 v31, v31, v35
	v_add_f32_e32 v29, v42, v37
	v_add_f32_e32 v37, v44, v31
	v_add_f32_e32 v31, v51, v31
	v_add_f32_e32 v38, v59, v31
	v_add_f32_e32 v31, v43, v31
	v_add_f32_e32 v27, v27, v31
	v_pk_add_f32 v[28:29], v[40:41], v[28:29]
	v_mul_f32_e32 v27, 0x3fb8aa3b, v27
	v_exp_f32_e32 v39, v27
	v_add_f32_e32 v27, v58, v31
	v_pk_add_f32 v[96:97], v[28:29], v[34:35]
	v_add_f32_e32 v26, v26, v27
	v_add_f32_e32 v27, v36, v97
	v_add_f32_e32 v28, v33, v27
	v_add_f32_e32 v27, v30, v27
	v_add_f32_e32 v29, v32, v27
	v_add_f32_e32 v27, v50, v27
	v_mul_f32_e32 v28, 0x3fb8aa3b, v28
	v_mul_f32_e32 v29, 0x3fb8aa3b, v29
	v_add_f32_e32 v4, v4, v27
	v_exp_f32_e32 v28, v28
	v_add_f32_e32 v3, v3, v4
	v_exp_f32_e32 v4, v29
	v_add_f32_e32 v30, v49, v27
	v_mul_f32_e32 v37, 0x3fb8aa3b, v37
	v_mul_f32_e32 v38, 0x3fb8aa3b, v38
	v_mul_f32_e32 v26, 0x3fb8aa3b, v26
	v_mul_f32_e32 v30, 0x3fb8aa3b, v30
	v_mul_f32_e32 v3, 0x3fb8aa3b, v3
	v_exp_f32_e32 v37, v37
	v_exp_f32_e32 v30, v30
	v_exp_f32_e32 v3, v3
	v_exp_f32_e32 v29, v26
	v_exp_f32_e32 v31, v38
	v_cvt_pk_bf16_f32 v27, v4, v28
	v_add_f32_e32 v4, v64, v5
	v_add_f32_e32 v5, v63, v5
	v_add_f32_e32 v46, v61, v5
	v_add_f32_e32 v5, v60, v5
	v_add_f32_e32 v47, v53, v65
	v_add_f32_e32 v62, v62, v5
	v_add_f32_e32 v5, v67, v5
	v_cvt_pk_bf16_f32 v26, v3, v30
	v_cvt_pk_bf16_f32 v28, v29, v39
	v_cvt_pk_bf16_f32 v29, v31, v37
	ds_read_b64_tr_b16 v[42:43], v110
	ds_read_b64_tr_b16 v[44:45], v114
	ds_read_b64_tr_b16 v[38:39], v111
	ds_read_b64_tr_b16 v[40:41], v115
	ds_read_b64_tr_b16 v[34:35], v112
	ds_read_b64_tr_b16 v[36:37], v116
	ds_read_b64_tr_b16 v[30:31], v113
	ds_read_b64_tr_b16 v[32:33], v117
	s_waitcnt lgkmcnt(0)
	v_add_f32_e32 v3, v52, v47
	v_add_f32_e32 v5, v66, v5
	v_mul_f32_e32 v3, 0x3fb8aa3b, v3
	v_mul_f32_e32 v4, 0x3fb8aa3b, v4
	v_mul_f32_e32 v70, 0x3fb8aa3b, v46
	ds_read_b64_tr_b16 v[58:59], v118
	ds_read_b64_tr_b16 v[60:61], v122
	ds_read_b64_tr_b16 v[54:55], v119
	ds_read_b64_tr_b16 v[56:57], v123
	ds_read_b64_tr_b16 v[50:51], v120
	ds_read_b64_tr_b16 v[52:53], v124
	ds_read_b64_tr_b16 v[46:47], v121
	ds_read_b64_tr_b16 v[48:49], v125
	s_waitcnt lgkmcnt(0)
	v_mul_f32_e32 v62, 0x3fb8aa3b, v62
	v_mul_f32_e32 v5, 0x3fb8aa3b, v5
	v_exp_f32_e32 v4, v4
	v_exp_f32_e32 v71, v62
	v_mfma_f32_16x16x32_bf16 v[66:69], v[50:53], v[26:29], 0
	v_exp_f32_e32 v5, v5
	v_exp_f32_e32 v50, v70
	v_exp_f32_e32 v3, v3
	v_mfma_f32_16x16x32_bf16 v[42:45], v[42:45], v[26:29], 0
	v_cvt_pk_bf16_f32 v70, v5, v71
	v_cvt_pk_bf16_f32 v71, v50, v4
	v_cvt_pk_bf16_f32 v72, v3, v72
	v_mfma_f32_16x16x32_bf16 v[38:41], v[38:41], v[26:29], 0
	v_cvt_pk_bf16_f32 v73, v92, v73
	v_mfma_f32_16x16x32_bf16 v[34:37], v[34:37], v[26:29], 0
	v_mfma_f32_16x16x32_bf16 v[30:33], v[30:33], v[26:29], 0
	v_mfma_f32_16x16x32_bf16 v[58:61], v[58:61], v[26:29], 0
	v_mfma_f32_16x16x32_bf16 v[62:65], v[54:57], v[26:29], 0
	v_mfma_f32_16x16x32_bf16 v[26:29], v[46:49], v[26:29], 0
	ds_read_b64_tr_b16 v[54:55], v126
	ds_read_b64_tr_b16 v[56:57], v130
	ds_read_b64_tr_b16 v[50:51], v127
	ds_read_b64_tr_b16 v[52:53], v131
	ds_read_b64_tr_b16 v[46:47], v128
	ds_read_b64_tr_b16 v[48:49], v132
	ds_read_b64_tr_b16 v[92:93], v129
	ds_read_b64_tr_b16 v[94:95], v133
	s_waitcnt lgkmcnt(0)
	s_nop 0
	v_mfma_f32_16x16x32_bf16 v[54:57], v[54:57], v[70:73], v[42:45]
	v_mfma_f32_16x16x32_bf16 v[50:53], v[50:53], v[70:73], v[38:41]
	v_mfma_f32_16x16x32_bf16 v[46:49], v[46:49], v[70:73], v[34:37]
	v_mfma_f32_16x16x32_bf16 v[42:45], v[92:95], v[70:73], v[30:33]
	ds_read_b64_tr_b16 v[38:39], v134
	ds_read_b64_tr_b16 v[40:41], v138
	ds_read_b64_tr_b16 v[34:35], v135
	ds_read_b64_tr_b16 v[36:37], v139
	ds_read_b64_tr_b16 v[30:31], v136
	ds_read_b64_tr_b16 v[32:33], v140
	ds_read_b64_tr_b16 v[92:93], v137
	ds_read_b64_tr_b16 v[94:95], v141
	s_waitcnt lgkmcnt(0)
	s_nop 0
	v_mfma_f32_16x16x32_bf16 v[38:41], v[38:41], v[70:73], v[58:61]
	v_mfma_f32_16x16x32_bf16 v[34:37], v[34:37], v[70:73], v[62:65]
	v_mfma_f32_16x16x32_bf16 v[30:33], v[30:33], v[70:73], v[66:69]
	v_mfma_f32_16x16x32_bf16 v[26:29], v[92:95], v[70:73], v[26:29]
	v_add_f32_e32 v93, v96, v97
	v_cmp_gt_f32_e32 vcc, s55, v93
	s_cmp_eq_u64 vcc, exec
	s_cselect_b64 s[0:1], -1, 0
	s_and_saveexec_b64 s[2:3], s[10:11]
	s_cbranch_execnz .LBB0_1900
	s_branch .LBB0_1901

; #define LAS __attribute__((address_space(3)))
; #define MFMA16(a, b, c) __builtin_amdgcn_mfma_f32_16x16x32_bf16((a), (b), (c), 0, 0, 0)
; __device__ __forceinline__ void attn_phase(Frame& F, bf16* OZ) {
;     ...
;         for (int kb = 0; kb < nkb; ++kb) {
;             const int spos0 = !smp ? (2 * qb + 1 - kb) * 64 : (kb == 0 ? 1024 : 1024 - 64 * kb), nvalid = (smp && kb == 0) ? 16 : 64;
;             if (kb > 0) { ATT_LOAD_KV(kb); __syncthreads(); }
;             bool done = true;
;             const bool none_visible = spos0 > __builtin_amdgcn_readfirstlane(tpos - l15) + 14;
;             if (active && none_visible) done = false;
;             if (active && !none_visible) {
;                 f32x4 sc[4];
; #pragma unroll
;                 for (int sb = 0; sb < 4; ++sb) { sc[sb] = (f32x4){0.f, 0.f, 0.f, 0.f};
; #pragma unroll
;                     for (int ks = 0; ks < 4; ++ks) { const bf16x8 a = *(const LAS bf16x8*)(L + KS + (16 * sb + l15) * ST_ + (32 * ks + 8 * g4) * 2); sc[sb] = MFMA16(a, qf[ks], sc[sb]); } }
;                 float lk[4][4], tsum[4], above[4], ttot[4];
; #pragma unroll
;                 for (int sb = 0; sb < 4; ++sb) { tsum[sb] = 0.f;
; #pragma unroll
;                     for (int e = 0; e < 4; ++e) { const int s = 16 * sb + 4 * g4 + e; const float z = sc[sb][e]; const bool vis = (s < nvalid) && (spos0 + s < tpos);
;                         const float sp = fmaxf(z, 0.f) + __logf(1.0f + __expf(-fabsf(z)));
;                         lk[sb][e] = vis ? -sp : 0.f; sc[sb][e] = vis ? z - sp : -1e30f; tsum[sb] += lk[sb][e]; }
.LBB0_1910:
	s_add_i32 s1, s60, s21
	s_and_b64 s[18:19], s[38:39], exec
	s_cselect_b32 s18, s0, s1
	v_readfirstlane_b32 s0, v150
	s_add_i32 s0, s0, 14
	s_cmp_gt_i32 s18, s0
	s_cselect_b64 s[0:1], -1, 0
	s_andn2_b64 s[0:1], s[0:1], s[64:65]
	s_or_b64 s[24:25], s[42:43], s[0:1]
	s_or_b64 s[24:25], s[24:25], s[64:65]
	s_and_b64 vcc, exec, s[24:25]
	s_waitcnt vmcnt(3)
	ds_write_b128 v144, v[58:61] offset:34816
	s_waitcnt vmcnt(2)
	ds_write_b128 v144, v[62:65] offset:52224
	s_waitcnt vmcnt(1)
	ds_write_b128 v145, v[66:69] offset:34816
	s_waitcnt vmcnt(0)
	ds_write_b128 v145, v[70:73] offset:52224
	s_waitcnt lgkmcnt(0)
	s_barrier
	s_cbranch_vccnz .LBB0_1912
	ds_read_b128 v[58:61], v146 offset:34816
	ds_read_b128 v[62:65], v146 offset:34880
	ds_read_b128 v[66:69], v146 offset:39168
	ds_read_b128 v[70:73], v146 offset:39232
	ds_read_b128 v[94:97], v146 offset:34944
	v_and_b32_e32 v5, 64, v147
	s_waitcnt lgkmcnt(4)
	v_mfma_f32_16x16x32_bf16 v[58:61], v[58:61], v[10:13], 0
	v_xor_b32_e32 v4, 16, v147
	v_add_u32_e32 v5, 64, v5
	v_cmp_lt_i32_e32 vcc, v4, v5
	s_waitcnt lgkmcnt(3)
	v_mfma_f32_16x16x32_bf16 v[58:61], v[62:65], v[14:17], v[58:61]
	ds_read_b128 v[62:65], v146 offset:35008
	ds_read_b128 v[154:157], v146 offset:39296
	ds_read_b128 v[158:161], v146 offset:39360
	v_cndmask_b32_e32 v4, v147, v4, vcc
	s_waitcnt lgkmcnt(5)
	v_mfma_f32_16x16x32_bf16 v[66:69], v[66:69], v[10:13], 0
	s_waitcnt lgkmcnt(3)
	v_mfma_f32_16x16x32_bf16 v[58:61], v[94:97], v[18:21], v[58:61]
	ds_read_b128 v[94:97], v146 offset:43520
	ds_read_b128 v[162:165], v146 offset:43584
	ds_read_b128 v[166:169], v146 offset:43648
	ds_read_b128 v[170:173], v146 offset:43712
	ds_read_b128 v[174:177], v146 offset:47872
	ds_read_b128 v[178:181], v146 offset:47936
	ds_read_b128 v[184:187], v146 offset:48000
	ds_read_b128 v[188:191], v146 offset:48064
	s_waitcnt lgkmcnt(10)
	v_mfma_f32_16x16x32_bf16 v[62:65], v[62:65], v[22:25], v[58:61]
	v_mfma_f32_16x16x32_bf16 v[58:61], v[70:73], v[14:17], v[66:69]
	s_waitcnt lgkmcnt(9)
	v_mfma_f32_16x16x32_bf16 v[58:61], v[154:157], v[18:21], v[58:61]
	v_lshlrev_b32_e32 v156, 2, v4
	v_xor_b32_e32 v4, 32, v147
	v_cmp_lt_i32_e32 vcc, v4, v5
	s_waitcnt lgkmcnt(8)
	v_mfma_f32_16x16x32_bf16 v[58:61], v[158:161], v[22:25], v[58:61]
	v_or_b32_e32 v158, s18, v1
	v_cndmask_b32_e32 v4, v147, v4, vcc
	v_lshlrev_b32_e32 v154, 2, v4
	v_xor_b32_e32 v4, 48, v147
	v_cmp_lt_i32_e32 vcc, v4, v5
	s_waitcnt lgkmcnt(7)
	v_mfma_f32_16x16x32_bf16 v[66:69], v[94:97], v[10:13], 0
	v_or_b32_e32 v159, s18, v86
	v_cndmask_b32_e32 v4, v147, v4, vcc
	v_lshlrev_b32_e32 v155, 2, v4
	v_mul_f32_e64 v4, |v62|, s49
	v_exp_f32_e32 v4, v4
	s_waitcnt lgkmcnt(6)
	v_mfma_f32_16x16x32_bf16 v[66:69], v[162:165], v[14:17], v[66:69]
	v_or_b32_e32 v162, s18, v88
	v_add_f32_e32 v4, 1.0, v4
	s_waitcnt lgkmcnt(5)
	v_mfma_f32_16x16x32_bf16 v[66:69], v[166:169], v[18:21], v[66:69]
	v_log_f32_e32 v4, v4
	v_max_f32_e32 v5, 0, v62
	s_waitcnt lgkmcnt(4)
	v_mfma_f32_16x16x32_bf16 v[70:73], v[170:173], v[22:25], v[66:69]
	v_mul_f32_e32 v92, 0x3f317217, v4
	v_fma_f32 v92, v4, s53, -v92
	v_fmac_f32_e32 v92, 0x3377d1cf, v4
	v_fma_f32 v4, v4, s53, v92
	s_waitcnt lgkmcnt(3)
	v_mfma_f32_16x16x32_bf16 v[66:69], v[174:177], v[10:13], 0
	v_mul_f32_e64 v92, |v63|, s49
	v_exp_f32_e32 v92, v92
	v_add_f32_e32 v4, v5, v4
	v_sub_f32_e32 v161, v62, v4
	v_sub_f32_e32 v160, 0, v4
	v_add_f32_e32 v4, 1.0, v92
	v_max_f32_e32 v62, 0, v63
	v_log_f32_e32 v4, v4
	v_or_b32_e32 v5, s18, v98
	s_waitcnt lgkmcnt(2)
	v_mfma_f32_16x16x32_bf16 v[66:69], v[178:181], v[14:17], v[66:69]
	v_mul_f32_e32 v92, 0x3f317217, v4
	v_fma_f32 v92, v4, s53, -v92
	v_fmac_f32_e32 v92, 0x3377d1cf, v4
	v_fma_f32 v4, v4, s53, v92
	s_waitcnt lgkmcnt(1)
	v_mfma_f32_16x16x32_bf16 v[66:69], v[184:187], v[18:21], v[66:69]
	v_cmp_lt_i32_e32 vcc, v5, v90
	v_mul_f32_e64 v5, |v64|, s49
	v_exp_f32_e32 v5, v5
	v_add_f32_e32 v62, v62, v4
	v_cndmask_b32_e64 v4, 0, -v62, vcc
	v_sub_f32_e32 v62, v63, v62
	v_add_f32_e32 v5, 1.0, v5
	v_cndmask_b32_e32 v157, v149, v62, vcc
	v_mul_f32_e64 v92, |v65|, s49
	v_exp_f32_e32 v92, v92
	v_log_f32_e32 v5, v5
	v_max_f32_e32 v94, 0, v64
	s_waitcnt lgkmcnt(0)
	v_mfma_f32_16x16x32_bf16 v[66:69], v[188:191], v[22:25], v[66:69]
	v_mul_f32_e32 v62, 0x3f317217, v5
	v_fma_f32 v62, v5, s53, -v62
	v_fmac_f32_e32 v62, 0x3377d1cf, v5
	v_fma_f32 v5, v5, s53, v62
	v_or_b32_e32 v63, s18, v75
	s_nop 0
	v_mov_b32_e32 v96, v5
	v_add_f32_e32 v5, 1.0, v92
	v_max_f32_e32 v92, 0, v65
	v_log_f32_e32 v5, v5
	v_or_b32_e32 v62, s18, v99
	v_mul_f32_e32 v95, 0x3f317217, v5
	v_fma_f32 v95, v5, s53, -v95
	v_fmac_f32_e32 v95, 0x3377d1cf, v5
	v_fma_f32 v5, v5, s53, v95
	s_nop 1
	v_add_f32_e32 v5, v92, v5
	v_mul_f32_e64 v92, |v58|, s49
	v_exp_f32_e32 v92, v92
	v_cmp_lt_i32_e32 vcc, v62, v90
	v_max_f32_e32 v95, 0, v58
	s_nop 0
	v_cndmask_b32_e64 v62, 0, -v5, vcc
	v_sub_f32_e32 v5, v65, v5
	v_cndmask_b32_e32 v65, v149, v5, vcc
	v_add_f32_e32 v5, 1.0, v92
	s_nop 1
	v_log_f32_e32 v5, v5
	v_or_b32_e32 v92, s18, v100
	v_mul_f32_e32 v97, 0x3f317217, v5
	v_fma_f32 v97, v5, s53, -v97
	v_fmac_f32_e32 v97, 0x3377d1cf, v5
	v_fma_f32 v5, v5, s53, v97
	s_nop 1
	v_add_f32_e32 v5, v95, v5
	v_mul_f32_e64 v95, |v59|, s49
	v_exp_f32_e32 v95, v95
	v_sub_f32_e32 v58, v58, v5
	v_cmp_lt_i32_e32 vcc, v92, v90
	v_sub_f32_e32 v5, 0, v5
	s_nop 0
	v_cndmask_b32_e32 v163, v149, v58, vcc
	v_add_f32_e32 v58, 1.0, v95
	v_cndmask_b32_e32 v5, 0, v5, vcc
	v_max_f32_e32 v95, 0, v59
	v_log_f32_e32 v58, v58
	v_or_b32_e32 v92, s18, v101
	v_mul_f32_e32 v97, 0x3f317217, v58
	v_fma_f32 v97, v58, s53, -v97
	v_fmac_f32_e32 v97, 0x3377d1cf, v58
	v_fma_f32 v58, v58, s53, v97
	s_nop 1
	v_add_f32_e32 v58, v95, v58
; __device__ __forceinline__ void attn_phase(Frame& F, bf16* OZ) {
;     ...
;                     for (int e = 0; e < 4; ++e) { const int s = 16 * sb + 4 * g4 + e; const float z = sc[sb][e]; const bool vis = (s < nvalid) && (spos0 + s < tpos);
;                         const float sp = fmaxf(z, 0.f) + __logf(1.0f + __expf(-fabsf(z)));
;                         lk[sb][e] = vis ? -sp : 0.f; sc[sb][e] = vis ? z - sp : -1e30f; tsum[sb] += lk[sb][e]; }
;                     const float v1 = __shfl_xor(tsum[sb], 16), v2 = __shfl_xor(tsum[sb], 32), v3 = __shfl_xor(tsum[sb], 48);
;                     above[sb] = ((g4 ^ 1) > g4 ? v1 : 0.f) + ((g4 ^ 2) > g4 ? v2 : 0.f) + ((g4 ^ 3) > g4 ? v3 : 0.f);
;                     ttot[sb] = (tsum[sb] + v1) + (v2 + v3); }
	v_mul_f32_e64 v95, |v60|, s49
	v_exp_f32_e32 v95, v95
	v_cmp_lt_i32_e32 vcc, v92, v90
	s_nop 1
	v_cndmask_b32_e64 v166, 0, -v58, vcc
	v_sub_f32_e32 v58, v59, v58
	v_cndmask_b32_e32 v167, v149, v58, vcc
	v_add_f32_e32 v58, 1.0, v95
	v_cmp_gt_f32_e32 vcc, s52, v58
	v_add_f32_e32 v5, v166, v5
	s_nop 0
	v_cndmask_b32_e64 v59, 0, 32, vcc
	v_ldexp_f32 v58, v58, v59
	v_log_f32_e32 v58, v58
	v_cndmask_b32_e32 v95, 0, v148, vcc
	v_max_f32_e32 v59, 0, v60
	v_mul_f32_e32 v92, 0x3f317217, v58
	v_fma_f32 v92, v58, s53, -v92
	v_fmac_f32_e32 v92, 0x3377d1cf, v58
	v_fmac_f32_e32 v92, 0x3f317217, v58
	v_cmp_lt_f32_e64 s[0:1], |v58|, s54
	s_nop 1
	v_cndmask_b32_e64 v58, v58, v92, s[0:1]
	v_mul_f32_e64 v92, |v61|, s49
	v_exp_f32_e32 v92, v92
	v_sub_f32_e32 v58, v58, v95
	v_add_f32_e32 v165, v59, v58
	v_sub_f32_e32 v168, v60, v165
	v_add_f32_e32 v58, 1.0, v92
	v_mul_f32_e64 v60, |v70|, s49
	v_exp_f32_e32 v60, v60
	v_log_f32_e32 v58, v58
	v_max_f32_e32 v95, 0, v61
	v_mul_f32_e32 v59, 0x3f317217, v58
	v_fma_f32 v59, v58, s53, -v59
	v_fmac_f32_e32 v59, 0x3377d1cf, v58
	v_fma_f32 v58, v58, s53, v59
	s_nop 1
	v_mov_b32_e32 v97, v58
	v_add_f32_e32 v58, 1.0, v60
	v_max_f32_e32 v60, 0, v70
	v_log_f32_e32 v58, v58
	v_or_b32_e32 v59, s18, v102
	v_mul_f32_e32 v92, 0x3f317217, v58
	v_fma_f32 v92, v58, s53, -v92
	v_fmac_f32_e32 v92, 0x3377d1cf, v58
	v_fma_f32 v58, v58, s53, v92
	s_nop 1
	v_add_f32_e32 v58, v60, v58
	v_sub_f32_e32 v60, v70, v58
	v_mul_f32_e64 v70, |v71|, s49
	v_exp_f32_e32 v70, v70
	v_cmp_lt_i32_e32 vcc, v59, v90
	v_sub_f32_e32 v58, 0, v58
	v_add_f32_e32 v59, 1.0, v70
	v_cndmask_b32_e32 v169, v149, v60, vcc
	v_cndmask_b32_e32 v58, 0, v58, vcc
	v_max_f32_e32 v70, 0, v71
	v_log_f32_e32 v59, v59
	v_or_b32_e32 v60, s18, v103
	v_mul_f32_e32 v92, 0x3f317217, v59
	v_fma_f32 v92, v59, s53, -v92
	v_fmac_f32_e32 v92, 0x3377d1cf, v59
	v_fma_f32 v59, v59, s53, v92
	s_nop 1
	v_cmp_lt_i32_e32 vcc, v60, v90
	v_mul_f32_e64 v60, |v72|, s49
	v_exp_f32_e32 v60, v60
	v_add_f32_e32 v59, v70, v59
	v_cndmask_b32_e64 v170, 0, -v59, vcc
	v_sub_f32_e32 v59, v71, v59
	v_cndmask_b32_e32 v171, v149, v59, vcc
	v_add_f32_e32 v59, 1.0, v60
	v_max_f32_e32 v70, 0, v72
	v_log_f32_e32 v59, v59
	v_or_b32_e32 v60, s18, v104
	v_add_f32_e32 v58, v170, v58
	v_mul_f32_e32 v71, 0x3f317217, v59
	v_fma_f32 v71, v59, s53, -v71
	v_fmac_f32_e32 v71, 0x3377d1cf, v59
	v_fma_f32 v59, v59, s53, v71
	s_nop 1
	v_cmp_lt_i32_e32 vcc, v60, v90
	v_mul_f32_e64 v60, |v73|, s49
	v_exp_f32_e32 v60, v60
	v_add_f32_e32 v59, v70, v59
	v_cndmask_b32_e64 v172, 0, -v59, vcc
	v_sub_f32_e32 v59, v72, v59
	v_cndmask_b32_e32 v173, v149, v59, vcc
	v_add_f32_e32 v59, 1.0, v60
	v_max_f32_e32 v70, 0, v73
	v_log_f32_e32 v59, v59
	v_or_b32_e32 v60, s18, v105
	v_add_f32_e32 v58, v172, v58
	v_mul_f32_e32 v71, 0x3f317217, v59
	v_fma_f32 v71, v59, s53, -v71
	v_fmac_f32_e32 v71, 0x3377d1cf, v59
	v_fma_f32 v59, v59, s53, v71
	s_nop 1
	v_add_f32_e32 v71, v70, v59
	v_cmp_lt_i32_e32 vcc, v60, v90
	v_sub_f32_e32 v60, v73, v71
	s_nop 0
	v_cndmask_b32_e64 v174, 0, -v71, vcc
	v_add_f32_e32 v58, v174, v58
	ds_bpermute_b32 v59, v154, v58
	ds_bpermute_b32 v70, v156, v58
	ds_bpermute_b32 v71, v155, v58
	v_cndmask_b32_e32 v175, v149, v60, vcc
	v_mul_f32_e64 v60, |v66|, s49
	v_exp_f32_e32 v60, v60
	s_waitcnt lgkmcnt(2)
	v_cndmask_b32_e64 v72, 0, v59, s[6:7]
	s_waitcnt lgkmcnt(0)
	v_pk_add_f32 v[58:59], v[58:59], v[70:71]
	v_cndmask_b32_e64 v92, 0, v71, s[8:9]
	v_pk_add_f32 v[58:59], v[58:59], v[58:59] op_sel_hi:[0,1]
	v_add_f32_e32 v58, 1.0, v60
	v_cndmask_b32_e64 v164, 0, v70, s[4:5]
	v_log_f32_e32 v58, v58
	v_max_f32_e32 v70, 0, v66
	v_or_b32_e32 v60, s18, v106
	v_mul_f32_e32 v71, 0x3f317217, v58
	v_fma_f32 v71, v58, s53, -v71
	v_fmac_f32_e32 v71, 0x3377d1cf, v58
	v_fma_f32 v58, v58, s53, v71
	s_nop 1
	v_add_f32_e32 v58, v70, v58
	v_mul_f32_e64 v70, |v67|, s49
	v_exp_f32_e32 v70, v70
	v_sub_f32_e32 v66, v66, v58
	v_cmp_lt_i32_e32 vcc, v60, v90
	v_sub_f32_e32 v58, 0, v58
	v_add_f32_e32 v60, 1.0, v70
	v_cndmask_b32_e32 v176, v149, v66, vcc
	v_cndmask_b32_e32 v58, 0, v58, vcc
	v_max_f32_e32 v70, 0, v67
	v_log_f32_e32 v60, v60
	v_or_b32_e32 v66, s18, v107
	v_mul_f32_e32 v71, 0x3f317217, v60
	v_fma_f32 v71, v60, s53, -v71
	v_fmac_f32_e32 v71, 0x3377d1cf, v60
	v_fma_f32 v60, v60, s53, v71
	s_nop 1
	v_cmp_lt_i32_e32 vcc, v66, v90
	v_mul_f32_e64 v66, |v68|, s49
	v_exp_f32_e32 v66, v66
	v_add_f32_e32 v60, v70, v60
	v_cndmask_b32_e64 v177, 0, -v60, vcc
	v_sub_f32_e32 v60, v67, v60
	v_add_f32_e32 v66, 1.0, v66
	v_cndmask_b32_e32 v60, v149, v60, vcc
	v_max_f32_e32 v70, 0, v68
	v_log_f32_e32 v66, v66
	v_or_b32_e32 v67, s18, v108
	v_add_f32_e32 v58, v177, v58
	v_mul_f32_e32 v71, 0x3f317217, v66
	v_fma_f32 v71, v66, s53, -v71
	v_fmac_f32_e32 v71, 0x3377d1cf, v66
	v_fma_f32 v66, v66, s53, v71
	s_nop 1
	v_cmp_lt_i32_e32 vcc, v67, v90
	v_mul_f32_e64 v67, |v69|, s49
	v_exp_f32_e32 v67, v67
	v_add_f32_e32 v66, v70, v66
	v_cndmask_b32_e64 v70, 0, -v66, vcc
	v_sub_f32_e32 v66, v68, v66
	v_cndmask_b32_e32 v71, v149, v66, vcc
	v_add_f32_e32 v66, 1.0, v67
	v_max_f32_e32 v68, 0, v69
	v_log_f32_e32 v66, v66
	v_or_b32_e32 v67, s18, v109
	v_add_f32_e32 v58, v70, v58
	v_cmp_lt_i32_e64 s[18:19], v158, v3
	v_mul_f32_e32 v73, 0x3f317217, v66
	v_fma_f32 v73, v66, s53, -v73
	v_fmac_f32_e32 v73, 0x3377d1cf, v66
	v_fma_f32 v66, v66, s53, v73
	s_nop 1
	v_add_f32_e32 v73, v68, v66
	v_cmp_lt_i32_e32 vcc, v67, v90
	v_cmp_lt_i32_e64 s[0:1], v162, v90
	s_nop 0
	v_cndmask_b32_e64 v178, 0, -v73, vcc
	v_add_f32_e32 v66, v178, v58
	ds_bpermute_b32 v67, v154, v66
	ds_bpermute_b32 v68, v156, v66
	v_sub_f32_e32 v58, v69, v73
	ds_bpermute_b32 v69, v155, v66
	v_cndmask_b32_e32 v58, v149, v58, vcc
	s_waitcnt lgkmcnt(2)
; __device__ __forceinline__ unsigned pk2(float lo, float hi) { const cvt_f2 v = {lo, hi}; const cvt_b2 r = __builtin_convertvector(v, cvt_b2); return __builtin_bit_cast(unsigned, r); }
; #define MFMA16(a, b, c) __builtin_amdgcn_mfma_f32_16x16x32_bf16((a), (b), (c), 0, 0, 0)
; __device__ __forceinline__ void attn_phase(Frame& F, bf16* OZ) {
;     ...
;                     const float v1 = __shfl_xor(tsum[sb], 16), v2 = __shfl_xor(tsum[sb], 32), v3 = __shfl_xor(tsum[sb], 48);
;                     above[sb] = ((g4 ^ 1) > g4 ? v1 : 0.f) + ((g4 ^ 2) > g4 ? v2 : 0.f) + ((g4 ^ 3) > g4 ? v3 : 0.f);
;                     ttot[sb] = (tsum[sb] + v1) + (v2 + v3); }
;                 float after = carry;
; #pragma unroll
;     ...
; #pragma unroll
;                     for (int e = 3; e >= 0; --e) { const float w = __expf(sc[sb][e] + run); run += lk[sb][e]; sc[sb][e] = w; }
;                     after += ttot[sb]; }
;                 carry = after;
; #pragma unroll
;                 for (int kk = 0; kk < 2; ++kk) { v4u pkd; pkd.x = pk2(sc[2 * kk][0], sc[2 * kk][1]); pkd.y = pk2(sc[2 * kk][2], sc[2 * kk][3]); pkd.z = pk2(sc[2 * kk + 1][0], sc[2 * kk + 1][1]); pkd.w = pk2(sc[2 * kk + 1][2], sc[2 * kk + 1][3]);
;                     const bf16x8 pf = __builtin_bit_cast(bf16x8, pkd);
; #pragma unroll
;                     for (int dh = 0; dh < 2; ++dh) { unsigned aa[4]; bf16x8 vf[4];
; #pragma unroll
;                         for (int i = 0; i < 4; ++i) aa[i] = F.lds0 + VS + (32 * kk + 4 * g4 + q) * ST_ + (32 * (2 * dh + (i >> 1)) + 8 * p + 4 * (i & 1)) * 2;
;                         tr_read_x4(aa, 16 * ST_, vf);
; #pragma unroll
;                         for (int i = 0; i < 4; ++i) oacc[4 * dh + i] = MFMA16(vf[i], pf, oacc[4 * dh + i]); } }
;                 done = __all(carry < ATT_THR);
	v_cndmask_b32_e64 v73, 0, v67, s[6:7]
	s_waitcnt lgkmcnt(1)
	v_cndmask_b32_e64 v179, 0, v68, s[4:5]
	v_add_f32_e32 v73, v179, v73
	s_waitcnt lgkmcnt(0)
	v_cndmask_b32_e64 v179, 0, v69, s[8:9]
	v_add_f32_e32 v73, v73, v179
	v_pk_add_f32 v[66:67], v[66:67], v[68:69]
	v_add_f32_e32 v68, v93, v73
	v_add_f32_e32 v58, v58, v68
	v_mul_f32_e32 v58, 0x3fb8aa3b, v58
	v_exp_f32_e32 v179, v58
	v_add_f32_e32 v58, v178, v68
	v_add_f32_e32 v68, v71, v58
	v_mul_f32_e32 v68, 0x3fb8aa3b, v68
	v_cmp_lt_i32_e32 vcc, v159, v90
	v_exp_f32_e32 v178, v68
	v_add_f32_e32 v180, v70, v58
	v_cndmask_b32_e32 v159, v149, v161, vcc
	v_pk_add_f32 v[68:69], v[94:95], v[96:97]
	v_cndmask_b32_e64 v71, 0, -v165, s[18:19]
	v_cndmask_b32_e32 v70, 0, v160, vcc
	v_cmp_lt_i32_e32 vcc, v63, v3
	v_pk_add_f32 v[94:95], v[70:71], v[4:5]
	v_cndmask_b32_e64 v96, 0, -v68, s[0:1]
	v_cndmask_b32_e64 v97, 0, -v69, vcc
	v_pk_add_f32 v[94:95], v[96:97], v[94:95]
	ds_bpermute_b32 v63, v156, v95
	v_mov_b32_e32 v165, v66
	v_mov_b32_e32 v73, v67
	v_add_f32_e32 v58, v60, v180
	v_pk_add_f32 v[66:67], v[164:165], v[72:73]
	v_mul_f32_e32 v58, 0x3fb8aa3b, v58
	v_pk_add_f32 v[66:67], v[66:67], v[92:93]
	ds_bpermute_b32 v92, v154, v95
	v_exp_f32_e32 v181, v58
	v_sub_f32_e32 v58, v64, v68
	s_waitcnt lgkmcnt(1)
	v_pk_add_f32 v[72:73], v[62:63], v[94:95]
	v_sub_f32_e32 v61, v61, v69
	ds_bpermute_b32 v69, v155, v95
	v_cndmask_b32_e64 v64, v149, v58, s[0:1]
	ds_bpermute_b32 v60, v156, v72
	ds_bpermute_b32 v58, v154, v72
	v_add_f32_e32 v5, v66, v67
	ds_bpermute_b32 v66, v155, v72
	v_cndmask_b32_e32 v93, v149, v61, vcc
	v_cndmask_b32_e64 v61, 0, v63, s[4:5]
	s_waitcnt lgkmcnt(4)
	v_cndmask_b32_e64 v63, 0, v92, s[6:7]
	v_add_f32_e32 v61, v61, v63
	s_waitcnt lgkmcnt(3)
	v_cndmask_b32_e64 v63, 0, v69, s[8:9]
	s_waitcnt lgkmcnt(2)
	v_cndmask_b32_e64 v68, 0, v60, s[4:5]
	s_waitcnt lgkmcnt(1)
	v_cndmask_b32_e64 v70, 0, v58, s[6:7]
	v_add_f32_e32 v63, v61, v63
	v_add_f32_e32 v61, v92, v69
	v_add_f32_e32 v68, v68, v70
	s_waitcnt lgkmcnt(0)
	v_cndmask_b32_e64 v70, 0, v66, s[8:9]
	v_pk_add_f32 v[60:61], v[72:73], v[60:61]
	v_pk_add_f32 v[58:59], v[58:59], v[66:67]
	v_add_f32_e32 v68, v68, v70
	v_pk_add_f32 v[154:155], v[60:61], v[58:59]
	v_add_f32_e32 v63, v63, v59
	v_add_f32_e32 v58, v68, v155
	v_cndmask_b32_e64 v70, v149, v168, s[18:19]
	v_add_f32_e32 v66, v93, v63
	v_add_f32_e32 v63, v97, v63
	v_add_f32_e32 v59, v65, v58
	v_add_f32_e32 v58, v62, v58
	v_add_f32_e32 v67, v70, v63
	v_add_f32_e32 v63, v71, v63
	v_add_f32_e32 v60, v64, v58
	v_add_f32_e32 v58, v96, v58
	v_add_f32_e32 v69, v167, v63
	v_add_f32_e32 v63, v166, v63
	v_add_f32_e32 v4, v4, v58
	v_add_f32_e32 v63, v163, v63
	v_add_f32_e32 v61, v157, v58
	v_add_f32_e32 v4, v159, v4
	v_mul_f32_e32 v66, 0x3fb8aa3b, v66
	v_mul_f32_e32 v67, 0x3fb8aa3b, v67
	v_mul_f32_e32 v69, 0x3fb8aa3b, v69
	v_mul_f32_e32 v63, 0x3fb8aa3b, v63
	v_mul_f32_e32 v59, 0x3fb8aa3b, v59
	v_mul_f32_e32 v60, 0x3fb8aa3b, v60
	v_mul_f32_e32 v61, 0x3fb8aa3b, v61
	v_mul_f32_e32 v4, 0x3fb8aa3b, v4
	v_exp_f32_e32 v66, v66
	v_exp_f32_e32 v69, v69
	v_exp_f32_e32 v59, v59
	v_exp_f32_e32 v61, v61
	v_exp_f32_e32 v4, v4
	v_exp_f32_e32 v60, v60
	v_exp_f32_e32 v62, v63
	v_exp_f32_e32 v63, v67
	v_cvt_pk_bf16_f32 v58, v4, v61
	v_cvt_pk_bf16_f32 v59, v60, v59
	v_cvt_pk_bf16_f32 v60, v62, v69
	v_cvt_pk_bf16_f32 v61, v63, v66
	ds_read_b64_tr_b16 v[206:207], v110
	ds_read_b64_tr_b16 v[208:209], v114
	ds_read_b64_tr_b16 v[210:211], v111
	ds_read_b64_tr_b16 v[212:213], v115
	ds_read_b64_tr_b16 v[214:215], v112
	ds_read_b64_tr_b16 v[216:217], v116
	ds_read_b64_tr_b16 v[218:219], v113
	ds_read_b64_tr_b16 v[220:221], v117
	ds_read_b64_tr_b16 v[222:223], v118
	ds_read_b64_tr_b16 v[224:225], v122
	ds_read_b64_tr_b16 v[226:227], v119
	ds_read_b64_tr_b16 v[228:229], v123
	ds_read_b64_tr_b16 v[230:231], v120
	ds_read_b64_tr_b16 v[232:233], v124
	ds_read_b64_tr_b16 v[234:235], v121
	s_waitcnt lgkmcnt(7)
	ds_read_b64_tr_b16 v[236:237], v125
	s_nop 0
	v_add_f32_e32 v156, v177, v180
	v_add_f32_e32 v4, v176, v156
	v_mfma_f32_16x16x32_bf16 v[54:57], v[206:209], v[58:61], v[54:57]
	v_add_f32_e32 v92, v175, v5
	v_add_f32_e32 v5, v174, v5
	v_mul_f32_e32 v4, 0x3fb8aa3b, v4
	v_mfma_f32_16x16x32_bf16 v[50:53], v[210:213], v[58:61], v[50:53]
	v_mul_f32_e32 v70, 0x3fb8aa3b, v92
	v_exp_f32_e32 v96, v70
	v_exp_f32_e32 v4, v4
	v_mfma_f32_16x16x32_bf16 v[46:49], v[214:217], v[58:61], v[46:49]
	v_add_f32_e32 v66, v173, v5
	v_mul_f32_e32 v97, 0x3fb8aa3b, v66
	v_add_f32_e32 v5, v172, v5
	v_mfma_f32_16x16x32_bf16 v[42:45], v[218:221], v[58:61], v[42:45]
	ds_read_b64_tr_b16 v[206:207], v126
	ds_read_b64_tr_b16 v[208:209], v130
	ds_read_b64_tr_b16 v[210:211], v127
	ds_read_b64_tr_b16 v[212:213], v131
	ds_read_b64_tr_b16 v[214:215], v128
	ds_read_b64_tr_b16 v[216:217], v132
	ds_read_b64_tr_b16 v[218:219], v129
	s_waitcnt lgkmcnt(7)
	ds_read_b64_tr_b16 v[220:221], v133
	s_nop 0
	s_nop 0
	v_mfma_f32_16x16x32_bf16 v[38:41], v[222:225], v[58:61], v[38:41]
	v_add_f32_e32 v92, v171, v5
	v_add_f32_e32 v5, v170, v5
	v_add_f32_e32 v5, v169, v5
	v_mul_f32_e32 v92, 0x3fb8aa3b, v92
	v_mul_f32_e32 v5, 0x3fb8aa3b, v5
	v_exp_f32_e32 v92, v92
	v_mfma_f32_16x16x32_bf16 v[30:33], v[230:233], v[58:61], v[30:33]
	v_exp_f32_e32 v5, v5
	v_exp_f32_e32 v66, v97
	v_mfma_f32_16x16x32_bf16 v[34:37], v[226:229], v[58:61], v[34:37]
	v_mfma_f32_16x16x32_bf16 v[26:29], v[234:237], v[58:61], v[26:29]
	v_cvt_pk_bf16_f32 v58, v5, v92
	v_cvt_pk_bf16_f32 v59, v66, v96
	v_cvt_pk_bf16_f32 v60, v4, v181
	v_cvt_pk_bf16_f32 v61, v178, v179
	ds_read_b64_tr_b16 v[222:223], v134
	ds_read_b64_tr_b16 v[224:225], v138
	ds_read_b64_tr_b16 v[226:227], v135
	ds_read_b64_tr_b16 v[228:229], v139
	ds_read_b64_tr_b16 v[230:231], v136
	ds_read_b64_tr_b16 v[232:233], v140
	ds_read_b64_tr_b16 v[234:235], v137
	s_waitcnt lgkmcnt(7)
	ds_read_b64_tr_b16 v[236:237], v141
	s_nop 0
	s_nop 1
	v_mfma_f32_16x16x32_bf16 v[54:57], v[206:209], v[58:61], v[54:57]
	v_mfma_f32_16x16x32_bf16 v[50:53], v[210:213], v[58:61], v[50:53]
	v_mfma_f32_16x16x32_bf16 v[46:49], v[214:217], v[58:61], v[46:49]
	v_mfma_f32_16x16x32_bf16 v[42:45], v[218:221], v[58:61], v[42:45]
	s_waitcnt lgkmcnt(0)
	s_nop 0
	s_nop 0
	v_mfma_f32_16x16x32_bf16 v[38:41], v[222:225], v[58:61], v[38:41]
	v_add_f32_e32 v93, v154, v155
	v_cmp_gt_f32_e32 vcc, s55, v93
	s_cmp_eq_u64 vcc, exec
	v_mfma_f32_16x16x32_bf16 v[34:37], v[226:229], v[58:61], v[34:37]
	s_cselect_b64 s[0:1], -1, 0
	s_mov_b64 s[64:65], s[0:1]
	v_mfma_f32_16x16x32_bf16 v[30:33], v[230:233], v[58:61], v[30:33]
	v_mfma_f32_16x16x32_bf16 v[26:29], v[234:237], v[58:61], v[26:29]
	s_and_saveexec_b64 s[18:19], s[10:11]
	s_cbranch_execz .LBB0_1905
	s_branch .LBB0_1913
